# B-branch prep: gamma loads hoisted out of per-token loops; c_q token prefetched one ahead
# speedup vs baseline: 1.0163x; 1.0010x over previous
; __device__ __forceinline__ int fresh_tid() { int t = threadIdx.x; asm volatile("" : "+v"(t)); return t; }
; __device__ __forceinline__ void b_prep1_cq(KP P, int l, int s_, int lane) {
;     const bf16_t* proj = (const bf16_t*)(P->ws + W_PROJ);
;     float a[8];
; #pragma unroll
;     for (int e = 0; e < 8; ++e) a[e] = 0.f;
;     if (lane < 56) ld8(proj + (size_t)s_ * NP + O_BCQ + lane * 8, a);
;     float ss = 0.f;
; #pragma unroll
;     for (int e = 0; e < 8; ++e) ss += a[e] * a[e];
;     const float rs = rsqrtf(wave_sum(ss) * (1.f / 448) + EPS);
;     if (lane < 56) {
; #pragma unroll
;         for (int e = 0; e < 8; ++e) a[e] *= rs * P->in[6][l * 448 + lane * 8 + e]; }
; __global__ void __launch_bounds__(512, 2) fwd_mega(Params Pk) {
;     ...
;         { const int tid = fresh_tid(), lane = tid & 63, gw = bid * 8 + (tid >> 6); for (int it = gw; it < SEQ; it += ngw) b_prep1_cq(P, l, it, lane); for (int it = gw; it < SEQ / 4; it += ngw) b_prep1_ckv(P, l, it, lane); }
.LBB0_529:
	s_or_b64 exec, exec, s[6:7]
	v_mov_b32_e32 v2, v250
	v_readlane_b32 s6, v253, 2
	v_ashrrev_i32_e32 v6, 6, v2
	s_movk_i32 s4, 0x2000
	v_add_u32_e32 v16, s6, v6
	v_and_b32_e32 v17, 63, v2
	v_readlane_b32 s7, v253, 3
	v_cmp_gt_i32_e32 vcc, s4, v16
	s_and_saveexec_b64 s[6:7], vcc
	s_cbranch_execz .LBB0_536
	v_cmp_lt_i32_e64 s[42:43], v245, v187
	v_readlane_b32 s18, v255, 46
	v_readlane_b32 s19, v255, 47
	v_cndmask_b32_e64 v0, v185, v245, s[42:43]
	v_cmp_lt_i32_e64 s[42:43], v204, v187
	v_lshlrev_b32_e32 v18, 2, v0
	s_mul_i32 s24, s18, 0x1c0
	v_cndmask_b32_e64 v0, v185, v204, s[42:43]
	v_cmp_lt_i32_e64 s[42:43], v181, v187
	v_lshlrev_b32_e32 v19, 2, v0
	s_load_dwordx2 s[20:21], s[0:1], 0xf0
	v_cndmask_b32_e64 v0, v185, v181, s[42:43]
	v_cmp_lt_i32_e64 s[42:43], v252, v187
	v_lshlrev_b32_e32 v20, 2, v0
	v_readlane_b32 s18, v253, 2
	v_cndmask_b32_e64 v0, v185, v252, s[42:43]
	v_lshlrev_b32_e32 v21, 2, v0
	v_xor_b32_e32 v0, 16, v185
	v_cmp_lt_i32_e64 s[42:43], v0, v187
	v_ashrrev_i32_e32 v7, 31, v6
	v_readlane_b32 s19, v253, 3
	v_cndmask_b32_e64 v0, v185, v0, s[42:43]
	v_lshlrev_b32_e32 v22, 2, v0
	v_xor_b32_e32 v0, 32, v185
	v_lshl_add_u64 v[4:5], s[18:19], 0, v[6:7]
	v_lshlrev_b32_e32 v2, 4, v2
	v_cmp_lt_i32_e64 s[42:43], v0, v187
	v_lshlrev_b64 v[8:9], 10, v[4:5]
	v_and_b32_e32 v10, 0x3f0, v2
	v_cndmask_b32_e64 v0, v185, v0, s[42:43]
	v_or_b32_e32 v8, v8, v10
	v_lshlrev_b32_e32 v23, 2, v0
	v_lshl_add_u32 v0, v17, 3, s24
	v_mov_b32_e32 v11, v1
	s_waitcnt lgkmcnt(0)
	v_lshl_add_u64 v[2:3], s[20:21], 0, v[8:9]
	s_mov_b64 s[24:25], 0x2d700000
	v_lshl_add_u64 v[2:3], v[2:3], 0, s[24:25]
	v_mad_u64_u32 v[8:9], s[24:25], v4, s26, v[10:11]
	v_mad_i32_i24 v9, v5, s26, v9
	v_readlane_b32 s18, v255, 37
	v_lshl_add_u64 v[4:5], s[20:21], 0, v[8:9]
	s_mov_b64 s[20:21], 0x17b02800
	v_cmp_gt_u32_e32 vcc, 56, v17
	v_readlane_b32 s19, v255, 38
	v_lshl_add_u64 v[4:5], v[4:5], 0, s[20:21]
	s_mov_b64 s[20:21], 0
	v_mov_b32_e32 v7, v16
	s_load_dwordx2 s[34:35], s[0:1], 0x30
	v_mov_b32_e32 v46, 0
	v_mov_b32_e32 v47, 0
	v_mov_b32_e32 v48, 0
	v_mov_b32_e32 v49, 0
	s_waitcnt lgkmcnt(0)
	v_lshl_add_u64 v[44:45], v[0:1], 2, s[34:35]
	s_and_saveexec_b64 s[24:25], vcc
	s_cbranch_execz .Lmy_cq_pre
	global_load_dwordx4 v[36:39], v[44:45], off offset:16
	global_load_dwordx4 v[40:43], v[44:45], off
	global_load_dwordx4 v[46:49], v[4:5], off
.Lmy_cq_pre:
	s_or_b64 exec, exec, s[24:25]
	s_waitcnt vmcnt(0)
	s_branch .LBB0_532

; __device__ __forceinline__ void b_prep1_cq(KP P, int l, int s_, int lane) {
;     ...
;     if (lane < 56) ld8(proj + (size_t)s_ * NP + O_BCQ + lane * 8, a);
;     float ss = 0.f;
; #pragma unroll
;     for (int e = 0; e < 8; ++e) ss += a[e] * a[e];
;     const float rs = rsqrtf(wave_sum(ss) * (1.f / 448) + EPS);
;     if (lane < 56) {
; #pragma unroll
;         for (int e = 0; e < 8; ++e) a[e] *= rs * P->in[6][l * 448 + lane * 8 + e]; }
.LBB0_532:
	v_mov_b32_e32 v8, 0
	v_mov_b32_e32 v9, 0
	v_mov_b32_e32 v10, 0
	v_mov_b32_e32 v11, 0
	v_mov_b32_e32 v12, 0
	v_mov_b32_e32 v13, 0
	v_mov_b32_e32 v14, 0
	v_mov_b32_e32 v15, 0
	s_and_saveexec_b64 s[24:25], vcc
	s_cbranch_execz .LBB0_534
	s_waitcnt vmcnt(1)
	v_mov_b32_e32 v12, v46
	v_mov_b32_e32 v13, v47
	v_mov_b32_e32 v14, v48
	v_mov_b32_e32 v15, v49
	v_readlane_b32 s34, v255, 23
	v_readlane_b32 s35, v255, 24
	s_nop 3
	v_lshl_add_u64 v[44:45], v[4:5], 0, s[34:35]
	global_load_dwordx4 v[46:49], v[44:45], off
	v_lshlrev_b32_e32 v8, 16, v12
	v_and_b32_e32 v9, 0xffff0000, v12
	v_lshlrev_b32_e32 v10, 16, v13
	v_and_b32_e32 v11, 0xffff0000, v13
	v_lshlrev_b32_e32 v12, 16, v14
	v_and_b32_e32 v13, 0xffff0000, v14
	v_lshlrev_b32_e32 v14, 16, v15
	v_and_b32_e32 v15, 0xffff0000, v15
.LBB0_534:
	s_or_b64 exec, exec, s[24:25]
	v_mul_f32_e32 v24, v9, v9
	v_fmac_f32_e32 v24, v8, v8
	v_fmac_f32_e32 v24, v10, v10
	v_fmac_f32_e32 v24, v11, v11
	v_fmac_f32_e32 v24, v12, v12
	v_fmac_f32_e32 v24, v13, v13
	v_fmac_f32_e32 v24, v14, v14
	v_fmac_f32_e32 v24, v15, v15
	s_waitcnt lgkmcnt(0)
	ds_bpermute_b32 v25, v18, v24
	s_waitcnt lgkmcnt(0)
	v_add_f32_e32 v24, v24, v25
	ds_bpermute_b32 v25, v19, v24
	s_waitcnt lgkmcnt(0)
	v_add_f32_e32 v24, v24, v25
	ds_bpermute_b32 v25, v20, v24
	s_waitcnt lgkmcnt(0)
	v_add_f32_e32 v24, v24, v25
	ds_bpermute_b32 v25, v21, v24
	s_waitcnt lgkmcnt(0)
	v_add_f32_e32 v24, v24, v25
	ds_bpermute_b32 v25, v22, v24
	s_waitcnt lgkmcnt(0)
	v_add_f32_e32 v24, v24, v25
	ds_bpermute_b32 v25, v23, v24
	s_and_saveexec_b64 s[24:25], vcc
	s_cbranch_execz .LBB0_531
	s_waitcnt lgkmcnt(0)
	v_add_f32_e32 v24, v24, v25
	v_fmamk_f32 v24, v24, 0x3b124925, v242
	v_cmp_gt_f32_e64 s[42:43], s29, v24
	v_mul_f32_e32 v25, 0x4b800000, v24
	v_cndmask_b32_e64 v24, v24, v25, s[42:43]
	v_rsq_f32_e32 v24, v24
	v_mov_b32_e32 v28, v40
	v_mul_f32_e32 v25, 0x45800000, v24
	v_cndmask_b32_e64 v32, v24, v25, s[42:43]
	v_mov_b32_e32 v24, v36
	v_mov_b32_e32 v25, v37
	v_mov_b32_e32 v26, v38
	v_mov_b32_e32 v27, v39
	v_mov_b32_e32 v29, v41
	v_mov_b32_e32 v30, v42
	v_mov_b32_e32 v31, v43
	v_pk_mul_f32 v[24:25], v[32:33], v[24:25] op_sel_hi:[0,1]
	v_pk_mul_f32 v[28:29], v[32:33], v[28:29] op_sel_hi:[0,1]
	v_pk_mul_f32 v[8:9], v[8:9], v[28:29]
	v_pk_mul_f32 v[28:29], v[32:33], v[30:31] op_sel_hi:[0,1]
	v_pk_mul_f32 v[12:13], v[12:13], v[24:25]
	v_pk_mul_f32 v[24:25], v[32:33], v[26:27] op_sel_hi:[0,1]
	v_pk_mul_f32 v[10:11], v[10:11], v[28:29]
	v_pk_mul_f32 v[14:15], v[14:15], v[24:25]
	s_branch .LBB0_531

; __device__ __forceinline__ void b_prep2_item(KP P, int l, int s_, int lane) {
;     const bf16_t* proj = (const bf16_t*)(P->ws + W_PROJ);
;     const int h = lane >> 4, i = lane & 15;
;     const bool hasr = i < 8, isx1 = i < 4;
;     const float posf = (float)((const int*)P->in[1])[s_];
;     float cs[8], sn[8];
; #pragma unroll
;     for (int e = 0; e < 8; ++e) { const int fi = (i & 3) * 8 + e;
;         const float inv = exp2f(-(float)fi * 0.41524101186092029f);
;         const float ang = posf * inv;
;         const double t = (double)ang * 0.15915494309189535;
;         const float fr = (float)(t - __builtin_rint(t));
;         sn[e] = __builtin_amdgcn_sinf(fr); cs[e] = __builtin_amdgcn_cosf(fr); }
;     const bf16_t* qsrc = (const bf16_t*)(P->ws + W_QRAW) + (size_t)s_ * 768 + h * 192;
;     const bf16_t* ksrc = (const bf16_t*)(P->ws + W_KVRAW) + (size_t)s_ * 1024 + h * 256;
;     const bf16_t* krsrc = proj + (size_t)s_ * NP + O_BKR;
;     bf16_t* qd = (bf16_t*)(P->ws + W_QB) + ((size_t)h * SEQ + s_) * 192;
;     bf16_t* kd = (bf16_t*)(P->ws + W_KB) + ((size_t)h * SEQ + s_) * 192;
; #pragma unroll
;     for (int w = 0; w < 2; ++w) {
;         float a[8], ar[8];
; #pragma unroll
;         for (int e = 0; e < 8; ++e) ar[e] = 0.f;
;         ld8((w ? ksrc : qsrc) + i * 8, a);
;         if (hasr) ld8(w ? krsrc + i * 8 : qsrc + 128 + i * 8, ar);
;         float ss = 0.f;
; #pragma unroll
;         for (int e = 0; e < 8; ++e) ss += a[e] * a[e] + ar[e] * ar[e];
;         ss += __shfl_xor(ss, 1); ss += __shfl_xor(ss, 2); ss += __shfl_xor(ss, 4); ss += __shfl_xor(ss, 8);
;         const float rs = rsqrtf(ss * (1.f / 192) + EPS) * (w ? 1.f : 0.07216878364870322f * 1.4426950408889634f);
;         const float* gg = (w ? P->in[11] : P->in[10]) + l * 192;
;         float o[8];
; #pragma unroll
;         for (int e = 0; e < 8; ++e) { a[e] *= rs * gg[i * 8 + e]; ar[e] *= rs * gg[128 + (i & 7) * 8 + e]; }
.LBB0_1060:
	s_or_b64 exec, exec, s[0:1]
	s_mov_b64 s[0:1], s[94:95]
	v_mov_b32_e32 v0, v250
	s_waitcnt lgkmcnt(0)
	s_barrier
	v_readlane_b32 s6, v253, 2
	v_ashrrev_i32_e32 v2, 6, v0
	s_movk_i32 s4, 0x2000
	v_add_u32_e32 v44, s6, v2
	v_readlane_b32 s7, v253, 3
	v_cmp_gt_i32_e32 vcc, s4, v44
	s_and_saveexec_b64 s[6:7], vcc
	s_cbranch_execz .LBB0_1071
	v_and_b32_e32 v3, 63, v0
	v_lshlrev_b32_e32 v3, 3, v3
	v_and_b32_e32 v4, 24, v3
	v_cvt_f32_ubyte0_e32 v5, v4
	v_mul_f32_e32 v6, 0xbed49a78, v5
	s_mov_b32 s4, 0xc2fc0000
	v_cmp_gt_f32_e32 vcc, s4, v6
	s_load_dwordx2 s[20:21], s[0:1], 0xf0
	s_load_dwordx2 s[30:31], s[0:1], 0x8
	s_load_dwordx2 s[34:35], s[0:1], 0x50
	v_cndmask_b32_e32 v6, 0, v251, vcc
	v_fmac_f32_e32 v6, 0xbed49a78, v5
	v_exp_f32_e32 v5, v6
	v_or_b32_e32 v6, 1, v4
	v_cvt_f32_ubyte0_e32 v6, v6
	v_mul_f32_e32 v8, 0xbed49a78, v6
	v_cmp_gt_f32_e64 s[44:45], s4, v8
	v_readlane_b32 s18, v255, 46
	v_and_b32_e32 v7, 15, v0
	v_cndmask_b32_e64 v8, 0, v251, s[44:45]
	v_fmac_f32_e32 v8, 0xbed49a78, v6
	v_exp_f32_e32 v6, v8
	v_cndmask_b32_e32 v8, 0, v246, vcc
	v_ldexp_f32 v45, v5, v8
	v_cndmask_b32_e64 v5, 0, v246, s[44:45]
	v_ldexp_f32 v46, v6, v5
	v_or_b32_e32 v5, 2, v4
	v_cvt_f32_ubyte0_e32 v5, v5
	v_mul_f32_e32 v6, 0xbed49a78, v5
	v_cmp_gt_f32_e32 vcc, s4, v6
	v_bfe_u32 v9, v0, 4, 2
	v_readlane_b32 s19, v255, 47
	v_cndmask_b32_e32 v6, 0, v251, vcc
	v_fmac_f32_e32 v6, 0xbed49a78, v5
	v_exp_f32_e32 v5, v6
	v_or_b32_e32 v6, 3, v4
	v_cvt_f32_ubyte0_e32 v6, v6
	v_mul_f32_e32 v8, 0xbed49a78, v6
	v_cmp_gt_f32_e64 s[44:45], s4, v8
	s_mul_i32 s38, s18, 0xc0
	s_lshl_b64 s[24:25], s[38:39], 2
	v_cndmask_b32_e64 v8, 0, v251, s[44:45]
	v_fmac_f32_e32 v8, 0xbed49a78, v6
	v_exp_f32_e32 v6, v8
	v_cndmask_b32_e32 v8, 0, v246, vcc
	v_ldexp_f32 v47, v5, v8
	v_cndmask_b32_e64 v5, 0, v246, s[44:45]
	v_ldexp_f32 v48, v6, v5
	v_or_b32_e32 v5, 4, v4
	v_cvt_f32_ubyte0_e32 v5, v5
	v_mul_f32_e32 v6, 0xbed49a78, v5
	v_cmp_gt_f32_e32 vcc, s4, v6
	v_readlane_b32 s18, v253, 2
	s_waitcnt lgkmcnt(0)
	s_add_u32 s34, s34, s24
	v_cndmask_b32_e32 v6, 0, v251, vcc
	v_fmac_f32_e32 v6, 0xbed49a78, v5
	v_exp_f32_e32 v5, v6
	v_or_b32_e32 v6, 5, v4
	v_cvt_f32_ubyte0_e32 v6, v6
	v_mul_f32_e32 v8, 0xbed49a78, v6
	v_cmp_gt_f32_e64 s[44:45], s4, v8
	v_readlane_b32 s19, v253, 3
	s_addc_u32 s35, s35, s25
	v_cndmask_b32_e64 v8, 0, v251, s[44:45]
	v_fmac_f32_e32 v8, 0xbed49a78, v6
	v_exp_f32_e32 v6, v8
	v_cndmask_b32_e32 v8, 0, v246, vcc
	v_ldexp_f32 v49, v5, v8
	v_cndmask_b32_e64 v5, 0, v246, s[44:45]
	v_ldexp_f32 v50, v6, v5
	v_or_b32_e32 v5, 6, v4
	v_cvt_f32_ubyte0_e32 v5, v5
	v_mul_f32_e32 v6, 0xbed49a78, v5
	v_cmp_gt_f32_e32 vcc, s4, v6
	v_or_b32_e32 v4, 7, v4
	v_cvt_f32_ubyte0_e32 v4, v4
	v_cndmask_b32_e32 v6, 0, v251, vcc
	v_fmac_f32_e32 v6, 0xbed49a78, v5
	v_exp_f32_e32 v5, v6
	v_mul_f32_e32 v6, 0xbed49a78, v4
	v_cmp_gt_f32_e64 s[44:45], s4, v6
	v_and_b32_e32 v8, 56, v3
	v_ashrrev_i32_e32 v3, 31, v2
	v_cndmask_b32_e64 v6, 0, v251, s[44:45]
	v_fmac_f32_e32 v6, 0xbed49a78, v4
	v_exp_f32_e32 v4, v6
	v_cndmask_b32_e32 v6, 0, v246, vcc
	v_cmp_lt_i32_e32 vcc, v245, v187
	v_ldexp_f32 v51, v5, v6
	v_cndmask_b32_e64 v5, 0, v246, s[44:45]
	v_cndmask_b32_e32 v0, v185, v245, vcc
	v_cmp_lt_i32_e32 vcc, v204, v187
	v_lshlrev_b32_e32 v53, 2, v0
	v_ldexp_f32 v52, v4, v5
	v_cndmask_b32_e32 v0, v185, v204, vcc
	v_cmp_lt_i32_e32 vcc, v181, v187
	v_lshlrev_b32_e32 v54, 2, v0
	v_lshlrev_b32_e32 v4, 13, v9
	v_cndmask_b32_e32 v0, v185, v181, vcc
	v_cmp_lt_i32_e32 vcc, v252, v187
	v_lshlrev_b32_e32 v55, 2, v0
	v_mov_b32_e32 v5, v1
	v_cndmask_b32_e32 v0, v185, v252, vcc
	v_lshlrev_b32_e32 v56, 2, v0
	v_lshlrev_b32_e32 v0, 5, v7
	v_lshl_add_u64 v[2:3], s[18:19], 0, v[2:3]
	v_lshl_add_u64 v[18:19], s[34:35], 0, v[0:1]
	v_lshlrev_b32_e32 v0, 2, v8
	v_lshl_add_u64 v[4:5], v[2:3], 0, v[4:5]
	v_mov_b64_e32 v[10:11], s[20:21]
	v_lshl_add_u64 v[20:21], s[34:35], 0, v[0:1]
	v_mad_u64_u32 v[22:23], s[34:35], v4, s27, v[10:11]
	v_mad_i32_i24 v23, v5, s27, v23
	v_lshl_add_u64 v[24:25], v[2:3], 2, s[30:31]
	v_mad_u64_u32 v[4:5], s[30:31], v2, s26, v[10:11]
	v_mad_i32_i24 v5, v3, s26, v5
	s_mov_b64 s[30:31], 0x17b02c80
	v_lshl_add_u64 v[26:27], v[4:5], 0, s[30:31]
	v_lshlrev_b64 v[4:5], 11, v[2:3]
	v_lshl_or_b32 v4, v9, 9, v4
	v_mul_u32_u24_e32 v12, 0xc0, v9
	v_lshl_add_u64 v[4:5], s[20:21], 0, v[4:5]
	s_mov_b64 s[30:31], 0x2ef00000
	v_lshl_add_u64 v[28:29], v[4:5], 0, s[30:31]
	v_lshlrev_b32_e32 v4, 1, v12
	v_mov_b32_e32 v5, v1
	s_movk_i32 s4, 0x600
	v_mad_u64_u32 v[4:5], s[30:31], v2, s4, v[4:5]
	v_lshlrev_b32_e32 v6, 3, v7
	v_readlane_b32 s18, v255, 37
	v_mad_i32_i24 v5, v3, s4, v5
	v_cmp_gt_u32_e64 s[42:43], 8, v7
	v_cmp_gt_u32_e64 s[44:45], 4, v7
	v_lshlrev_b32_e32 v0, 4, v7
	v_readlane_b32 s19, v255, 38
	v_lshl_add_u64 v[30:31], s[20:21], 0, v[4:5]
	s_mov_b64 s[34:35], 0
	v_lshlrev_b32_e32 v57, 2, v6
	v_lshlrev_b32_e32 v58, 2, v8
	global_load_dwordx4 v[100:103], v[18:19], off offset:16
	global_load_dwordx4 v[104:107], v[18:19], off
	global_load_dwordx4 v[108:111], v[20:21], off offset:528
	global_load_dwordx4 v[112:115], v[20:21], off offset:512
	s_load_dwordx2 s[20:21], s[0:1], 0x58
	s_waitcnt lgkmcnt(0)
	s_add_u32 s20, s20, s24
	s_addc_u32 s21, s21, s25
	global_load_dwordx4 v[116:119], v57, s[20:21] offset:16
	global_load_dwordx4 v[120:123], v57, s[20:21]
	global_load_dwordx4 v[124:127], v58, s[20:21] offset:528
	global_load_dwordx4 v[128:131], v58, s[20:21] offset:512
	s_branch .LBB0_1063

; __device__ __forceinline__ void b_prep2_item(KP P, int l, int s_, int lane) {
;     ...
;     const float posf = (float)((const int*)P->in[1])[s_];
;     float cs[8], sn[8];
; #pragma unroll
;     for (int e = 0; e < 8; ++e) { const int fi = (i & 3) * 8 + e;
;         const float inv = exp2f(-(float)fi * 0.41524101186092029f);
;         const float ang = posf * inv;
;         const double t = (double)ang * 0.15915494309189535;
;         const float fr = (float)(t - __builtin_rint(t));
;         sn[e] = __builtin_amdgcn_sinf(fr); cs[e] = __builtin_amdgcn_cosf(fr); }
;     const bf16_t* qsrc = (const bf16_t*)(P->ws + W_QRAW) + (size_t)s_ * 768 + h * 192;
;     const bf16_t* ksrc = (const bf16_t*)(P->ws + W_KVRAW) + (size_t)s_ * 1024 + h * 256;
;     const bf16_t* krsrc = proj + (size_t)s_ * NP + O_BKR;
;     bf16_t* qd = (bf16_t*)(P->ws + W_QB) + ((size_t)h * SEQ + s_) * 192;
;     bf16_t* kd = (bf16_t*)(P->ws + W_KB) + ((size_t)h * SEQ + s_) * 192;
; #pragma unroll
;     for (int w = 0; w < 2; ++w) {
;         float a[8], ar[8];
; #pragma unroll
;         for (int e = 0; e < 8; ++e) ar[e] = 0.f;
;         ld8((w ? ksrc : qsrc) + i * 8, a);
;         if (hasr) ld8(w ? krsrc + i * 8 : qsrc + 128 + i * 8, ar);
;         float ss = 0.f;
; #pragma unroll
;         for (int e = 0; e < 8; ++e) ss += a[e] * a[e] + ar[e] * ar[e];
;         ss += __shfl_xor(ss, 1); ss += __shfl_xor(ss, 2); ss += __shfl_xor(ss, 4); ss += __shfl_xor(ss, 8);
;         const float rs = rsqrtf(ss * (1.f / 192) + EPS) * (w ? 1.f : 0.07216878364870322f * 1.4426950408889634f);
;         const float* gg = (w ? P->in[11] : P->in[10]) + l * 192;
;         float o[8];
; #pragma unroll
;         for (int e = 0; e < 8; ++e) { a[e] *= rs * gg[i * 8 + e]; ar[e] *= rs * gg[128 + (i & 7) * 8 + e]; }
; #pragma unroll
;         for (int e = 0; e < 8; ++e) { const float pr = __shfl_xor(ar[e], 4);
;             o[e] = isx1 ? ar[e] * cs[e] - pr * sn[e] : ar[e] * cs[e] + pr * sn[e]; }
;         bf16_t* dd = w ? kd : qd;
;         st8(dd + i * 8, a);
;         if (hasr) st8(dd + 128 + i * 8, o);
.LBB0_1065:
	s_or_b64 exec, exec, s[20:21]
	s_waitcnt vmcnt(1)
	v_cvt_f32_i32_e32 v10, v8
	s_waitcnt vmcnt(0)
	v_and_b32_e32 v77, 0xffff0000, v2
	v_and_b32_e32 v43, 0xffff0000, v3
	v_lshlrev_b32_e32 v42, 16, v3
	v_mul_f32_e32 v6, v45, v10
	v_cvt_f64_f32_e32 v[6:7], v6
	s_waitcnt lgkmcnt(3)
	v_mul_f64 v[8:9], v[6:7], s[36:37]
	v_rndne_f64_e32 v[8:9], v[8:9]
	v_fma_f64 v[6:7], v[6:7], s[36:37], -v[8:9]
	v_cvt_f32_f64_e32 v6, v[6:7]
	v_sin_f32_e32 v60, v6
	v_cos_f32_e32 v59, v6
	v_mul_f32_e32 v6, v46, v10
	v_cvt_f64_f32_e32 v[6:7], v6
	v_mul_f64 v[8:9], v[6:7], s[36:37]
	v_rndne_f64_e32 v[8:9], v[8:9]
	v_fma_f64 v[6:7], v[6:7], s[36:37], -v[8:9]
	v_cvt_f32_f64_e32 v6, v[6:7]
	v_sin_f32_e32 v62, v6
	v_cos_f32_e32 v61, v6
	v_mul_f32_e32 v6, v47, v10
	v_cvt_f64_f32_e32 v[6:7], v6
	v_mul_f64 v[8:9], v[6:7], s[36:37]
	v_rndne_f64_e32 v[8:9], v[8:9]
	v_fma_f64 v[6:7], v[6:7], s[36:37], -v[8:9]
	v_cvt_f32_f64_e32 v6, v[6:7]
	v_sin_f32_e32 v64, v6
	v_cos_f32_e32 v63, v6
	v_mul_f32_e32 v6, v48, v10
	v_cvt_f64_f32_e32 v[6:7], v6
	v_mul_f64 v[8:9], v[6:7], s[36:37]
	v_rndne_f64_e32 v[8:9], v[8:9]
	v_fma_f64 v[6:7], v[6:7], s[36:37], -v[8:9]
	v_cvt_f32_f64_e32 v6, v[6:7]
	v_sin_f32_e32 v66, v6
	v_cos_f32_e32 v65, v6
	v_mul_f32_e32 v6, v49, v10
	v_cvt_f64_f32_e32 v[6:7], v6
	v_mul_f64 v[8:9], v[6:7], s[36:37]
	v_rndne_f64_e32 v[8:9], v[8:9]
	v_fma_f64 v[6:7], v[6:7], s[36:37], -v[8:9]
	v_cvt_f32_f64_e32 v6, v[6:7]
	v_sin_f32_e32 v68, v6
	v_cos_f32_e32 v67, v6
	v_mul_f32_e32 v6, v50, v10
	v_cvt_f64_f32_e32 v[6:7], v6
	v_mul_f64 v[8:9], v[6:7], s[36:37]
	v_rndne_f64_e32 v[8:9], v[8:9]
	v_fma_f64 v[6:7], v[6:7], s[36:37], -v[8:9]
	v_cvt_f32_f64_e32 v6, v[6:7]
	v_sin_f32_e32 v70, v6
	v_cos_f32_e32 v69, v6
	v_mul_f32_e32 v6, v51, v10
	v_cvt_f64_f32_e32 v[6:7], v6
	v_mul_f64 v[8:9], v[6:7], s[36:37]
	v_rndne_f64_e32 v[8:9], v[8:9]
	v_fma_f64 v[6:7], v[6:7], s[36:37], -v[8:9]
	v_cvt_f32_f64_e32 v6, v[6:7]
	v_sin_f32_e32 v72, v6
	v_cos_f32_e32 v71, v6
	v_mul_f32_e32 v6, v52, v10
	v_cvt_f64_f32_e32 v[6:7], v6
	v_mul_f64 v[8:9], v[6:7], s[36:37]
	v_rndne_f64_e32 v[8:9], v[8:9]
	v_fma_f64 v[6:7], v[6:7], s[36:37], -v[8:9]
	v_cvt_f32_f64_e32 v6, v[6:7]
	v_lshlrev_b32_e32 v8, 16, v2
	v_mul_f32_e32 v2, v76, v76
	v_mul_f32_e32 v3, v75, v75
	v_sin_f32_e32 v74, v6
	v_cos_f32_e32 v73, v6
	v_fmac_f32_e32 v2, v8, v8
	v_fmac_f32_e32 v3, v77, v77
	v_pk_mul_f32 v[6:7], v[36:37], v[36:37]
	v_add_f32_e32 v9, v2, v3
	v_pk_fma_f32 v[6:7], v[42:43], v[42:43], v[6:7]
	v_and_b32_e32 v41, 0xffff0000, v4
	v_lshlrev_b32_e32 v40, 16, v4
	v_and_b32_e32 v39, 0xffff0000, v5
	v_lshlrev_b32_e32 v38, 16, v5
	v_pk_mul_f32 v[4:5], v[34:35], v[34:35]
	v_add_f32_e32 v6, v6, v9
	v_add_f32_e32 v6, v7, v6
	v_pk_fma_f32 v[4:5], v[40:41], v[40:41], v[4:5]
	v_pk_mul_f32 v[2:3], v[32:33], v[32:33]
	v_add_f32_e32 v4, v4, v6
	v_add_f32_e32 v4, v5, v4
	v_pk_fma_f32 v[2:3], v[38:39], v[38:39], v[2:3]
	s_nop 0
	v_add_f32_e32 v2, v2, v4
	v_add_f32_e32 v2, v3, v2
	ds_bpermute_b32 v3, v53, v2
	s_waitcnt lgkmcnt(0)
	v_add_f32_e32 v2, v2, v3
	ds_bpermute_b32 v3, v54, v2
	s_waitcnt lgkmcnt(0)
	v_add_f32_e32 v2, v2, v3
	ds_bpermute_b32 v3, v55, v2
	s_waitcnt lgkmcnt(0)
	v_add_f32_e32 v2, v2, v3
	ds_bpermute_b32 v3, v56, v2
	s_waitcnt lgkmcnt(0)
	v_add_f32_e32 v2, v2, v3
	v_fmamk_f32 v2, v2, 0x3baaaaab, v242
	v_cmp_gt_f32_e32 vcc, s29, v2
	v_mul_f32_e32 v3, 0x4b800000, v2
	s_nop 0
	v_cndmask_b32_e32 v2, v2, v3, vcc
	v_rsq_f32_e32 v2, v2
	s_nop 0
	v_mul_f32_e32 v3, 0x45800000, v2
	v_cndmask_b32_e32 v2, v2, v3, vcc
	v_mul_f32_e32 v78, 0x3dd53b94, v2
	v_mov_b32_e32 v2, v100
	v_mov_b32_e32 v3, v101
	v_mov_b32_e32 v4, v102
	v_mov_b32_e32 v5, v103
	v_mov_b32_e32 v10, v104
	v_mov_b32_e32 v11, v105
	v_mov_b32_e32 v12, v106
	v_mov_b32_e32 v13, v107
	v_mul_f32_e32 v2, v2, v78
	v_mul_f32_e32 v6, v10, v78
	v_mul_f32_e32 v79, v6, v8
	v_mov_b32_e32 v6, v108
	v_mov_b32_e32 v7, v109
	v_mov_b32_e32 v8, v110
	v_mov_b32_e32 v9, v111
	v_mov_b32_e32 v14, v112
	v_mov_b32_e32 v15, v113
	v_mov_b32_e32 v16, v114
	v_mov_b32_e32 v17, v115
	v_mul_f32_e32 v3, v3, v78
	v_mul_f32_e32 v10, v14, v78
	v_mul_f32_e32 v14, v76, v10
	v_mul_f32_e32 v10, v11, v78
	v_mul_f32_e32 v76, v10, v77
	v_mul_f32_e32 v10, v15, v78
	v_mul_f32_e32 v15, v75, v10
	v_mul_f32_e32 v10, v12, v78
	v_mul_f32_e32 v42, v10, v42
	v_mul_f32_e32 v10, v16, v78
	v_mul_f32_e32 v12, v36, v10
	v_mul_f32_e32 v10, v13, v78
	v_mul_f32_e32 v36, v10, v43
	v_mul_f32_e32 v10, v17, v78
	v_mul_f32_e32 v13, v37, v10
	v_mul_f32_e32 v37, v2, v40
	v_mul_f32_e32 v40, v3, v41
	v_mul_f32_e32 v3, v7, v78
	v_mul_f32_e32 v2, v6, v78
	v_mul_f32_e32 v6, v35, v3
	v_mul_f32_e32 v3, v4, v78
	v_mul_f32_e32 v38, v3, v38
	v_mul_f32_e32 v3, v8, v78
	v_mul_f32_e32 v8, v32, v3
	v_mul_f32_e32 v3, v5, v78
	v_mul_f32_e32 v39, v3, v39
	v_mul_f32_e32 v3, v9, v78
	v_mul_f32_e32 v2, v34, v2
	v_mul_f32_e32 v16, v33, v3
	ds_bpermute_b32 v3, v55, v14
	ds_bpermute_b32 v4, v55, v15
	ds_bpermute_b32 v5, v55, v12
	ds_bpermute_b32 v7, v55, v13
	ds_bpermute_b32 v9, v55, v2
	ds_bpermute_b32 v17, v55, v6
	ds_bpermute_b32 v32, v55, v8
	ds_bpermute_b32 v33, v55, v16
	v_lshl_add_u64 v[10:11], v[22:23], 0, v[0:1]
	s_nop 0
	v_cvt_pk_bf16_f32 v34, v79, v76
	s_nop 0
	v_cvt_pk_bf16_f32 v35, v42, v36
	s_nop 0
	v_cvt_pk_bf16_f32 v36, v37, v40
	s_nop 0
	v_cvt_pk_bf16_f32 v37, v38, v39
	v_add_co_u32_e32 v38, vcc, 0x2ff00000, v10
	s_nop 1
	v_addc_co_u32_e32 v39, vcc, 0, v11, vcc
	global_store_dwordx4 v[38:39], v[34:37], off
	s_and_saveexec_b64 s[20:21], s[42:43]
	s_cbranch_execz .LBB0_1067
	s_waitcnt lgkmcnt(0)
	v_mul_f32_e32 v33, v74, v33
	v_cndmask_b32_e64 v33, v33, -v33, s[44:45]
	v_fmac_f32_e32 v33, v73, v16
	v_mul_f32_e32 v16, v72, v32
	v_cndmask_b32_e64 v16, v16, -v16, s[44:45]
	v_fmac_f32_e32 v16, v71, v8
	v_mul_f32_e32 v8, v70, v17
	v_cndmask_b32_e64 v8, v8, -v8, s[44:45]
	v_fmac_f32_e32 v8, v69, v6
	v_mul_f32_e32 v6, v68, v9
	v_cndmask_b32_e64 v6, v6, -v6, s[44:45]
	v_fmac_f32_e32 v6, v67, v2
	v_mul_f32_e32 v2, v66, v7
	v_cndmask_b32_e64 v7, v2, -v2, s[44:45]
	v_mul_f32_e32 v2, v64, v5
	v_cndmask_b32_e64 v5, v2, -v2, s[44:45]
	v_mul_f32_e32 v2, v62, v4
	v_mul_f32_e32 v3, v60, v3
	v_cndmask_b32_e64 v2, v2, -v2, s[44:45]
	v_cndmask_b32_e64 v3, v3, -v3, s[44:45]
	v_fmac_f32_e32 v2, v61, v15
	v_fmac_f32_e32 v3, v59, v14
	v_fmac_f32_e32 v7, v65, v13
	v_fmac_f32_e32 v5, v63, v12
	s_nop 0
	v_cvt_pk_bf16_f32 v2, v3, v2
	s_nop 0
	v_cvt_pk_bf16_f32 v3, v5, v7
	s_nop 0
	v_cvt_pk_bf16_f32 v4, v6, v8
	v_add_co_u32_e32 v6, vcc, 0x2ff00000, v10
	s_nop 0
	v_cvt_pk_bf16_f32 v5, v16, v33
	s_nop 1
	v_addc_co_u32_e32 v7, vcc, 0, v11, vcc
	global_store_dwordx4 v[6:7], v[2:5], off offset:256

; __device__ __forceinline__ void b_prep2_item(KP P, int l, int s_, int lane) {
;     ...
;     for (int w = 0; w < 2; ++w) {
;         float a[8], ar[8];
; #pragma unroll
;         for (int e = 0; e < 8; ++e) ar[e] = 0.f;
;         ld8((w ? ksrc : qsrc) + i * 8, a);
;         if (hasr) ld8(w ? krsrc + i * 8 : qsrc + 128 + i * 8, ar);
;         float ss = 0.f;
; #pragma unroll
;         for (int e = 0; e < 8; ++e) ss += a[e] * a[e] + ar[e] * ar[e];
;         ss += __shfl_xor(ss, 1); ss += __shfl_xor(ss, 2); ss += __shfl_xor(ss, 4); ss += __shfl_xor(ss, 8);
;         const float rs = rsqrtf(ss * (1.f / 192) + EPS) * (w ? 1.f : 0.07216878364870322f * 1.4426950408889634f);
;         const float* gg = (w ? P->in[11] : P->in[10]) + l * 192;
;         float o[8];
; #pragma unroll
;         for (int e = 0; e < 8; ++e) { a[e] *= rs * gg[i * 8 + e]; ar[e] *= rs * gg[128 + (i & 7) * 8 + e]; }
; #pragma unroll
;         for (int e = 0; e < 8; ++e) { const float pr = __shfl_xor(ar[e], 4);
;             o[e] = isx1 ? ar[e] * cs[e] - pr * sn[e] : ar[e] * cs[e] + pr * sn[e]; }
;         bf16_t* dd = w ? kd : qd;
;         st8(dd + i * 8, a);
;         if (hasr) st8(dd + 128 + i * 8, o);
.LBB0_1069:
	s_or_b64 exec, exec, s[20:21]
	s_waitcnt vmcnt(0)
	v_lshlrev_b32_e32 v8, 16, v2
	v_and_b32_e32 v75, 0xffff0000, v2
	v_and_b32_e32 v37, 0xffff0000, v3
	v_lshlrev_b32_e32 v36, 16, v3
	v_mul_f32_e32 v2, v39, v39
	v_mul_f32_e32 v3, v38, v38
	v_fmac_f32_e32 v2, v8, v8
	v_fmac_f32_e32 v3, v75, v75
	v_pk_mul_f32 v[6:7], v[32:33], v[32:33]
	v_add_f32_e32 v9, v2, v3
	v_pk_fma_f32 v[6:7], v[36:37], v[36:37], v[6:7]
	v_and_b32_e32 v35, 0xffff0000, v4
	v_lshlrev_b32_e32 v34, 16, v4
	v_and_b32_e32 v17, 0xffff0000, v5
	v_lshlrev_b32_e32 v16, 16, v5
	v_pk_mul_f32 v[4:5], v[14:15], v[14:15]
	v_add_f32_e32 v6, v6, v9
	v_add_f32_e32 v6, v7, v6
	v_pk_fma_f32 v[4:5], v[34:35], v[34:35], v[4:5]
	v_pk_mul_f32 v[2:3], v[12:13], v[12:13]
	v_add_f32_e32 v4, v4, v6
	v_add_f32_e32 v4, v5, v4
	v_pk_fma_f32 v[2:3], v[16:17], v[16:17], v[2:3]
	s_load_dwordx2 s[20:21], s[0:1], 0x58
	v_add_f32_e32 v2, v2, v4
	v_add_f32_e32 v2, v3, v2
	ds_bpermute_b32 v3, v53, v2
	s_waitcnt lgkmcnt(0)
	s_add_u32 s20, s20, s24
	s_addc_u32 s21, s21, s25
	v_add_f32_e32 v2, v2, v3
	ds_bpermute_b32 v3, v54, v2
	s_waitcnt lgkmcnt(0)
	v_add_f32_e32 v2, v2, v3
	ds_bpermute_b32 v3, v55, v2
	s_waitcnt lgkmcnt(0)
	v_add_f32_e32 v2, v2, v3
	ds_bpermute_b32 v3, v56, v2
	s_waitcnt lgkmcnt(0)
	v_add_f32_e32 v2, v2, v3
	v_fmamk_f32 v2, v2, 0x3baaaaab, v242
	v_cmp_gt_f32_e32 vcc, s29, v2
	v_mul_f32_e32 v3, 0x4b800000, v2
	s_nop 0
	v_cndmask_b32_e32 v2, v2, v3, vcc
	v_rsq_f32_e32 v2, v2
	s_nop 0
	v_mul_f32_e32 v3, 0x45800000, v2
	v_cndmask_b32_e32 v80, v2, v3, vcc
	v_mov_b32_e32 v2, v116
	v_mov_b32_e32 v3, v117
	v_mov_b32_e32 v4, v118
	v_mov_b32_e32 v5, v119
	v_mov_b32_e32 v40, v120
	v_mov_b32_e32 v41, v121
	v_mov_b32_e32 v42, v122
	v_mov_b32_e32 v43, v123
	v_mul_f32_e32 v2, v2, v80
	v_mul_f32_e32 v6, v40, v80
	v_mul_f32_e32 v40, v6, v8
	v_mov_b32_e32 v6, v124
	v_mov_b32_e32 v7, v125
	v_mov_b32_e32 v8, v126
	v_mov_b32_e32 v9, v127
	v_mov_b32_e32 v76, v128
	v_mov_b32_e32 v77, v129
	v_mov_b32_e32 v78, v130
	v_mov_b32_e32 v79, v131
	v_mul_f32_e32 v42, v42, v80
	v_mul_f32_e32 v36, v42, v36
	v_mul_f32_e32 v41, v41, v80
	v_mul_f32_e32 v3, v3, v80
	v_mul_f32_e32 v4, v4, v80
	v_mul_f32_e32 v5, v5, v80
	v_mul_f32_e32 v41, v41, v75
	v_mul_f32_e32 v16, v4, v16
	v_mul_f32_e32 v17, v5, v17
	v_mul_f32_e32 v4, v8, v80
	v_mul_f32_e32 v42, v78, v80
	v_mul_f32_e32 v32, v32, v42
	v_mul_f32_e32 v42, v43, v80
	v_mul_f32_e32 v37, v42, v37
	v_mul_f32_e32 v42, v79, v80
	v_mul_f32_e32 v76, v76, v80
	v_mul_f32_e32 v75, v77, v80
	v_mul_f32_e32 v33, v33, v42
	v_mul_f32_e32 v42, v2, v34
	v_mul_f32_e32 v2, v6, v80
	v_mul_f32_e32 v43, v3, v35
	v_mul_f32_e32 v3, v7, v80
	v_mul_f32_e32 v5, v80, v9
	v_mul_f32_e32 v39, v39, v76
	v_mul_f32_e32 v38, v38, v75
	v_mul_f32_e32 v2, v14, v2
	v_mul_f32_e32 v3, v15, v3
	v_mul_f32_e32 v4, v12, v4
	v_mul_f32_e32 v12, v13, v5
	ds_bpermute_b32 v5, v55, v39
	ds_bpermute_b32 v6, v55, v38
	ds_bpermute_b32 v7, v55, v32
	ds_bpermute_b32 v8, v55, v33
	ds_bpermute_b32 v9, v55, v2
	ds_bpermute_b32 v13, v55, v3
	ds_bpermute_b32 v14, v55, v4
	ds_bpermute_b32 v15, v55, v12
	s_nop 0
	v_cvt_pk_bf16_f32 v34, v40, v41
	s_nop 0
	v_cvt_pk_bf16_f32 v35, v36, v37
	s_nop 0
	v_cvt_pk_bf16_f32 v36, v42, v43
	s_nop 0
	v_cvt_pk_bf16_f32 v37, v16, v17
	v_add_co_u32_e32 v16, vcc, 0x30b00000, v10
	s_nop 1
	v_addc_co_u32_e32 v17, vcc, 0, v11, vcc
	global_store_dwordx4 v[16:17], v[34:37], off
	s_and_saveexec_b64 s[20:21], s[42:43]
	s_cbranch_execz .LBB0_1062
	s_waitcnt lgkmcnt(0)
	v_mul_f32_e32 v15, v74, v15
	v_cndmask_b32_e64 v15, v15, -v15, s[44:45]
	v_fmac_f32_e32 v15, v73, v12
	v_mul_f32_e32 v12, v72, v14
	v_cndmask_b32_e64 v12, v12, -v12, s[44:45]
	v_fmac_f32_e32 v12, v71, v4
	v_mul_f32_e32 v4, v70, v13
	v_cndmask_b32_e64 v4, v4, -v4, s[44:45]
	v_fmac_f32_e32 v4, v69, v3
	v_mul_f32_e32 v3, v68, v9
	v_cndmask_b32_e64 v9, v3, -v3, s[44:45]
	v_fmac_f32_e32 v9, v67, v2
	v_mul_f32_e32 v2, v66, v8
	v_cndmask_b32_e64 v3, v2, -v2, s[44:45]
	v_mul_f32_e32 v2, v64, v7
	v_cndmask_b32_e64 v7, v2, -v2, s[44:45]
	v_mul_f32_e32 v2, v62, v6
	v_cndmask_b32_e64 v2, v2, -v2, s[44:45]
	v_mul_f32_e32 v5, v60, v5
	v_fmac_f32_e32 v3, v65, v33
	v_fmac_f32_e32 v7, v63, v32
	v_fmac_f32_e32 v2, v61, v38
	v_cndmask_b32_e64 v5, v5, -v5, s[44:45]
	v_add_co_u32_e32 v6, vcc, 0x30b00000, v10
	v_fmac_f32_e32 v5, v59, v39
	s_nop 0
	v_cvt_pk_bf16_f32 v2, v5, v2
	s_nop 0
	v_cvt_pk_bf16_f32 v3, v7, v3
	s_nop 0
	v_addc_co_u32_e32 v7, vcc, 0, v11, vcc
	s_nop 0
	v_cvt_pk_bf16_f32 v4, v9, v4
	s_nop 0
	v_cvt_pk_bf16_f32 v5, v12, v15
	global_store_dwordx4 v[6:7], v[2:5], off offset:256
	s_branch .LBB0_1062
